# layer-1 weight conversion spread over idle slots of layer 0 (down/out GEMM split-K tails, gate/up last round); only 192 tile units remain in layer 1's first norm phase
# baseline (speedup 1.0000x reference)
; __device__ __forceinline__ void convert_layer(PP P, int l, LAS unsigned char* lds, const Ids I) {
;     ...
;     for (int u = BID; u < 7 * 176 + 64; u += NB) {
;         const int mi = u / 176, uu = u - mi * 176;
;         if (mi == 0)      conv_tile4(P->in[I_F1G] + wl, 1024, 2816, (bf16_t*)(ws + WS_WGU1), 5, uu, T, I);
;         else if (mi == 1) conv_tile4(P->in[I_F1U] + wl, 1024, 2816, (bf16_t*)(ws + WS_WGU1), 6, uu, T, I);
;         else if (mi == 2) conv_tile4(P->in[I_F1D] + wl, 2816, 1024, (bf16_t*)(ws + WS_WD1), 0, uu, T, I);
;         else if (mi == 3) conv_tile4(P->in[I_WIN] + wl, 1024, 2816, (bf16_t*)(ws + WS_WIN), 4, uu, T, I);
;         else if (mi == 4) conv_tile4(P->in[I_F2G] + wl, 1024, 2816, (bf16_t*)(ws + WS_WGU2), 5, uu, T, I);
;         else if (mi == 5) conv_tile4(P->in[I_F2U] + wl, 1024, 2816, (bf16_t*)(ws + WS_WGU2), 6, uu, T, I);
;         else if (mi == 6) conv_tile4(P->in[I_F2D] + wl, 2816, 1024, (bf16_t*)(ws + WS_WD2), 0, uu, T, I);
;         else              conv_tile4(P->in[I_WOUT] + (size_t)l * 1024 * 1024, 1024, 1024, (bf16_t*)(ws + WS_WOUT), 0, uu, T, I);
;     }
; __global__ void __launch_bounds__(512) mega(Params Pval) {
;     ...
;             } else if (sub == 2 || sub == 8 || sub == 11) {
;                 const int gk = sub == 2 ? 2 : (sub == 8 ? 5 : 8);
;                 const float scl = sub == 8 ? 1.0f : 0.5f; const int Kd = sub == 8 ? 1024 : FF;
;                 EpiResid E{P->out, modl + gk * 1024, scl};
;                 const bf16_t* A = (const bf16_t*)(ws + (sub == 8 ? WS_HB : WS_R1)); const bf16_t* Bt = (const bf16_t*)(ws + (sub == 2 ? WS_WD1 : (sub == 8 ? WS_WOUT : WS_WD2)));
;                 run_gemm(lds, A, Bt, MTP, 1024, Kd, E, I);
;                 EpiPartial EA{(float*)(ws + WS_R2)};
;                 run_gemm_splitk(lds, A + (size_t)MTP * Kd, Bt, MTS, 1024, Kd, 256, EA, I);
.LBB0_393:
	s_cmp_eq_u32 s33, 4
	s_cbranch_scc1 .Lcv_c4
	s_cmp_eq_u32 s33, 10
	s_cbranch_scc1 .Lcv_c10
	s_cmp_eq_u32 s33, 13
	s_cbranch_scc0 .Lcv_none
	s_sub_i32 s6, s93, 0x58
	s_cmp_lt_i32 s6, 0
	s_cbranch_scc1 .Lcv_none
	s_mov_b32 s35, s22
	s_add_i32 s22, s6, 0x2c0
	s_movk_i32 s100, 0xa8
	s_branch .Lcv_go
.Lcv_c4:
	s_sub_i32 s6, s93, 0x58
	s_cmp_lt_i32 s6, 0
	s_cbranch_scc1 .Lcv_none
	s_mov_b32 s35, s22
	s_mov_b32 s22, s6
	s_movk_i32 s100, 0xa8
	s_branch .Lcv_go
.Lcv_c10:
	s_sub_i32 s6, s93, 32
	s_cmp_lt_i32 s6, 0
	s_cbranch_scc1 .Lcv_none
	s_mov_b32 s35, s22
	s_add_i32 s22, s6, 0x150
	s_movk_i32 s100, 0xe0
.Lcv_go:
	s_add_i32 s3, s22, 0xfffffbe0
	s_mov_b64 s[28:29], s[12:13]
	s_mov_b32 s31, s25
	s_mov_b64 s[26:27], 0xb00000
	s_branch .LBB0_504
.Lcv_ret2:
	s_mov_b64 s[12:13], s[28:29]
	s_mov_b32 s25, s31
	s_mov_b32 s22, s35
	v_readlane_b32 s27, v254, 47

; __device__ __forceinline__ void convert_layer(PP P, int l, LAS unsigned char* lds, const Ids I) {
;     ...
;     for (int u = BID; u < 7 * 176 + 64; u += NB) {
;         const int mi = u / 176, uu = u - mi * 176;
;         if (mi == 0)      conv_tile4(P->in[I_F1G] + wl, 1024, 2816, (bf16_t*)(ws + WS_WGU1), 5, uu, T, I);
;         else if (mi == 1) conv_tile4(P->in[I_F1U] + wl, 1024, 2816, (bf16_t*)(ws + WS_WGU1), 6, uu, T, I);
;         else if (mi == 2) conv_tile4(P->in[I_F1D] + wl, 2816, 1024, (bf16_t*)(ws + WS_WD1), 0, uu, T, I);
;         else if (mi == 3) conv_tile4(P->in[I_WIN] + wl, 1024, 2816, (bf16_t*)(ws + WS_WIN), 4, uu, T, I);
;         else if (mi == 4) conv_tile4(P->in[I_F2G] + wl, 1024, 2816, (bf16_t*)(ws + WS_WGU2), 5, uu, T, I);
;         else if (mi == 5) conv_tile4(P->in[I_F2U] + wl, 1024, 2816, (bf16_t*)(ws + WS_WGU2), 6, uu, T, I);
;         else if (mi == 6) conv_tile4(P->in[I_F2D] + wl, 2816, 1024, (bf16_t*)(ws + WS_WD2), 0, uu, T, I);
;         else              conv_tile4(P->in[I_WOUT] + (size_t)l * 1024 * 1024, 1024, 1024, (bf16_t*)(ws + WS_WOUT), 0, uu, T, I);
;     }
; __global__ void __launch_bounds__(512) mega(Params Pval) {
;     ...
;             } else if (sub == 1 || sub == 10) {
;                 EpiSwiGLU E{(bf16_t*)(ws + WS_R1)}; run_gemm(lds, (const bf16_t*)(ws + WS_HB), (const bf16_t*)(ws + (sub == 1 ? WS_WGU1 : WS_WGU2)), MT, 2 * FF, 1024, E, I);
.LBB0_412:
	v_readlane_b32 s30, v254, 45
	s_mov_b32 s25, s45
	v_readlane_b32 s27, v254, 47
	s_barrier
	s_cmp_eq_u32 s33, 12
	s_cbranch_scc0 .LBB0_413
	s_sub_i32 s6, s93, 0xac
	s_cmp_lt_u32 s6, 64
	s_cbranch_scc0 .LBB0_413
	s_mov_b64 s[28:29], s[12:13]
	s_add_i32 s22, s93, 0x424
	s_add_i32 s3, s93, 4
	s_movk_i32 s100, 0x100
	s_mov_b64 s[26:27], 0xb00000
	s_branch .LBB0_504

; __device__ __forceinline__ void convert_layer(PP P, int l, LAS unsigned char* lds, const Ids I) {
;     ...
;     for (int u = BID; u < 7 * 176 + 64; u += NB) {
;         const int mi = u / 176, uu = u - mi * 176;
;         if (mi == 0)      conv_tile4(P->in[I_F1G] + wl, 1024, 2816, (bf16_t*)(ws + WS_WGU1), 5, uu, T, I);
;         else if (mi == 1) conv_tile4(P->in[I_F1U] + wl, 1024, 2816, (bf16_t*)(ws + WS_WGU1), 6, uu, T, I);
;         else if (mi == 2) conv_tile4(P->in[I_F1D] + wl, 2816, 1024, (bf16_t*)(ws + WS_WD1), 0, uu, T, I);
;         else if (mi == 3) conv_tile4(P->in[I_WIN] + wl, 1024, 2816, (bf16_t*)(ws + WS_WIN), 4, uu, T, I);
;         else if (mi == 4) conv_tile4(P->in[I_F2G] + wl, 1024, 2816, (bf16_t*)(ws + WS_WGU2), 5, uu, T, I);
;         else if (mi == 5) conv_tile4(P->in[I_F2U] + wl, 1024, 2816, (bf16_t*)(ws + WS_WGU2), 6, uu, T, I);
;         else if (mi == 6) conv_tile4(P->in[I_F2D] + wl, 2816, 1024, (bf16_t*)(ws + WS_WD2), 0, uu, T, I);
;         else              conv_tile4(P->in[I_WOUT] + (size_t)l * 1024 * 1024, 1024, 1024, (bf16_t*)(ws + WS_WOUT), 0, uu, T, I);
;     }
; __global__ void __launch_bounds__(512) mega(Params Pval) {
;     ...
;                 if (sub == 0 && l == 1) convert_layer(P, 1, lds, I);
.LBB0_500:
	s_and_b64 vcc, exec, s[0:1]
	s_cbranch_vccz .LBB0_591
	s_cmp_eq_u32 s30, 0
	s_cselect_b64 s[0:1], -1, 0
	s_cmp_eq_u32 s43, 1
	s_cselect_b64 s[4:5], -1, 0
	v_readlane_b32 s8, v254, 16
	s_and_b64 s[6:7], s[0:1], s[4:5]
	v_readlane_b32 s9, v254, 17
	s_and_b64 s[6:7], s[8:9], s[6:7]
	s_andn2_b64 vcc, exec, s[6:7]
	s_mov_b64 s[26:27], 0xb00000
	s_cbranch_vccnz .LBB0_532
	s_cmpk_gt_u32 s93, 0xbf
	s_cbranch_scc1 .LBB0_532
	s_add_i32 s3, s93, 0xfffffff0
	s_add_i32 s22, s93, 0x410
	s_movk_i32 s100, 0x100
	s_branch .LBB0_504
.Lcv_exit:
	s_cmp_eq_u32 s33, 14
	s_cbranch_scc1 .LBB0_532
	s_cmp_eq_u32 s33, 12
	s_cbranch_scc1 .Lcv_ret1
	s_branch .Lcv_ret2
.LBB0_503:
	s_add_i32 s22, s22, s100
	s_add_i32 s3, s3, s100
	s_movk_i32 s6, 0x4d0
	s_cmp_eq_u32 s33, 4
	s_cselect_b32 s6, 0x150, s6
	s_cmp_eq_u32 s33, 10
	s_cselect_b32 s6, 0x2c0, s6
	s_cmp_eq_u32 s33, 12
	s_cselect_b32 s6, 0x510, s6
	s_cmp_eq_u32 s33, 13
	s_cselect_b32 s6, 0x410, s6
	s_cmp_lt_i32 s22, s6
	s_waitcnt lgkmcnt(0)
	s_cbranch_scc0 .Lcv_exit
